# prologue x->hb loop: wave_sum butterflies via DPP and permlane swaps instead of ds_bpermute
# speedup vs baseline: 1.0008x; 1.0008x over previous
; __device__ __forceinline__ float wave_sum(float v) {
; #pragma unroll
;     for (int o = 1; o < 64; o <<= 1) v += __shfl_xor(v, o);
;     return v;
; __device__ __forceinline__ void prologue(const Args& a, LAS unsigned char* lds, int w, int G, int wave, int lane) {
;     ...
;     for (int i = wave * 4; i < 256; i += NWAVES * 4) { const size_t row = (size_t)w * 256 + i;
;         const f32x4* xr = (const f32x4*)(a.x + row * D) + lane; f32x4 v[4][4]; float sq[4];
; #pragma unroll
;         for (int r = 0; r < 4; ++r)
; #pragma unroll
;             for (int j = 0; j < 4; ++j) v[r][j] = __builtin_nontemporal_load(xr + r * 256 + 64 * j);
; #pragma unroll
;         for (int r = 0; r < 4; ++r) { float s = 0.f;
; #pragma unroll
;             for (int j = 0; j < 4; ++j) s += (v[r][j][0] * v[r][j][0] + v[r][j][1] * v[r][j][1]) + (v[r][j][2] * v[r][j][2] + v[r][j][3] * v[r][j][3]);
;             sq[r] = wave_sum(s); }
; #pragma unroll
.LBB0_73:
	global_load_dwordx4 v[60:63], v[66:67], off nt
	global_load_dwordx4 v[56:59], v[66:67], off offset:1024 nt
	global_load_dwordx4 v[52:55], v[66:67], off offset:2048 nt
	global_load_dwordx4 v[48:51], v[66:67], off offset:3072 nt
	v_add_co_u32_e32 v0, vcc, 0x1000, v66
	s_waitcnt vmcnt(2)
	v_mul_f32_e32 v83, v57, v57
	v_addc_co_u32_e32 v1, vcc, 0, v67, vcc
	global_load_dwordx4 v[44:47], v[0:1], off nt
	global_load_dwordx4 v[40:43], v[0:1], off offset:1024 nt
	global_load_dwordx4 v[36:39], v[0:1], off offset:2048 nt
	global_load_dwordx4 v[32:35], v[0:1], off offset:3072 nt
	v_add_co_u32_e32 v0, vcc, 0x2000, v66
	s_waitcnt lgkmcnt(0)
	v_mul_f32_e32 v84, v59, v59
	v_addc_co_u32_e32 v1, vcc, 0, v67, vcc
	global_load_dwordx4 v[28:31], v[0:1], off nt
	global_load_dwordx4 v[24:27], v[0:1], off offset:1024 nt
	global_load_dwordx4 v[20:23], v[0:1], off offset:2048 nt
	global_load_dwordx4 v[16:19], v[0:1], off offset:3072 nt
	v_add_co_u32_e32 v72, vcc, 0x3000, v66
	s_waitcnt vmcnt(9)
	v_mul_f32_e32 v85, v53, v53
	v_addc_co_u32_e32 v73, vcc, 0, v67, vcc
	global_load_dwordx4 v[12:15], v[72:73], off nt
	global_load_dwordx4 v[8:11], v[72:73], off offset:1024 nt
	global_load_dwordx4 v[4:7], v[72:73], off offset:2048 nt
	global_load_dwordx4 v[0:3], v[72:73], off offset:3072 nt
	v_mul_f32_e32 v72, v61, v61
	v_mul_f32_e32 v73, v63, v63
	v_mul_f32_e32 v86, v55, v55
	v_fmac_f32_e32 v72, v60, v60
	v_fmac_f32_e32 v73, v62, v62
	v_fmac_f32_e32 v83, v56, v56
	v_fmac_f32_e32 v84, v58, v58
	s_waitcnt vmcnt(12)
	v_mul_f32_e32 v87, v49, v49
	v_mul_f32_e32 v88, v51, v51
	v_fmac_f32_e32 v85, v52, v52
	v_fmac_f32_e32 v86, v54, v54
	v_add_f32_e32 v72, v72, v73
	v_add_f32_e32 v73, v83, v84
	v_fmac_f32_e32 v87, v48, v48
	v_fmac_f32_e32 v88, v50, v50
	v_add_f32_e32 v83, v85, v86
	v_add_f32_e32 v72, v72, v73
	v_add_f32_e32 v84, v87, v88
	v_add_f32_e32 v72, v72, v83
	v_add_f32_e32 v72, v72, v84
	s_nop 1
	v_mov_b32_dpp v84, v72 quad_perm:[1,0,3,2] row_mask:0xf bank_mask:0xf
	v_cvt_pk_bf16_f32 v60, v60, v61
	v_cvt_pk_bf16_f32 v61, v62, v63
	s_waitcnt lgkmcnt(0)
	v_add_f32_e32 v72, v72, v84
	s_nop 1
	v_mov_b32_dpp v84, v72 quad_perm:[2,3,0,1] row_mask:0xf bank_mask:0xf
	s_waitcnt lgkmcnt(0)
	v_add_f32_e32 v72, v72, v84
	s_nop 1
	v_mov_b32_dpp v100, v72 row_half_mirror row_mask:0xf bank_mask:0xf
	s_nop 1
	v_mov_b32_dpp v84, v100 quad_perm:[3,2,1,0] row_mask:0xf bank_mask:0xf
	s_waitcnt lgkmcnt(0)
	v_add_f32_e32 v72, v72, v84
	s_nop 1
	v_mov_b32_dpp v84, v72 row_ror:8 row_mask:0xf bank_mask:0xf
	s_waitcnt lgkmcnt(0)
	v_add_f32_e32 v72, v72, v84
	v_mov_b32_e32 v84, v72
	v_mov_b32_e32 v100, v72
	s_nop 1
	v_permlane16_swap_b32_e32 v100, v84
	s_waitcnt vmcnt(11)
	v_mul_f32_e32 v85, v45, v45
	v_mul_f32_e32 v86, v47, v47
	s_waitcnt vmcnt(10)
	v_mul_f32_e32 v87, v41, v41
	v_mul_f32_e32 v88, v43, v43
	s_waitcnt vmcnt(9)
	v_mul_f32_e32 v89, v37, v37
	v_mul_f32_e32 v90, v39, v39
	v_fmac_f32_e32 v85, v44, v44
	v_fmac_f32_e32 v86, v46, v46
	v_fmac_f32_e32 v87, v40, v40
	v_fmac_f32_e32 v88, v42, v42
	s_waitcnt vmcnt(7)
	v_mul_f32_e32 v73, v29, v29
	v_mul_f32_e32 v93, v31, v31
	s_waitcnt vmcnt(6)
	v_mul_f32_e32 v94, v25, v25
	v_mul_f32_e32 v95, v27, v27
	v_mul_f32_e32 v91, v33, v33
	v_mul_f32_e32 v92, v35, v35
	v_fmac_f32_e32 v89, v36, v36
	v_fmac_f32_e32 v90, v38, v38
	s_waitcnt vmcnt(5)
	v_mul_f32_e32 v96, v21, v21
	v_mul_f32_e32 v97, v23, v23
	v_add_f32_e32 v83, v85, v86
	v_add_f32_e32 v85, v87, v88
	v_fmac_f32_e32 v73, v28, v28
	v_fmac_f32_e32 v93, v30, v30
	v_fmac_f32_e32 v94, v24, v24
	v_fmac_f32_e32 v95, v26, v26
	v_fmac_f32_e32 v91, v32, v32
	v_fmac_f32_e32 v92, v34, v34
	v_add_f32_e32 v86, v89, v90
	v_fmac_f32_e32 v96, v20, v20
	v_fmac_f32_e32 v97, v22, v22
	v_add_f32_e32 v83, v83, v85
	v_add_f32_e32 v73, v73, v93
	v_add_f32_e32 v85, v94, v95
	v_add_f32_e32 v87, v91, v92
	v_add_f32_e32 v88, v96, v97
	v_add_f32_e32 v83, v83, v86
	v_add_f32_e32 v73, v73, v85
	s_waitcnt vmcnt(3)
	v_mul_f32_e32 v89, v13, v13
	v_mul_f32_e32 v91, v15, v15
	v_add_f32_e32 v83, v83, v87
	v_add_f32_e32 v73, v73, v88
	s_waitcnt lgkmcnt(0)
	v_add_f32_e32 v88, v72, v84
	s_waitcnt vmcnt(2)
; __device__ __forceinline__ unsigned pk2(float lo, float hi) { return pg8::cvt_pk_bf16(lo, hi); }
; __device__ __forceinline__ void prologue(const Args& a, LAS unsigned char* lds, int w, int G, int wave, int lane) {
;     ...
;         for (int r = 0; r < 4; ++r) { float s = 0.f;
; #pragma unroll
;             for (int j = 0; j < 4; ++j) s += (v[r][j][0] * v[r][j][0] + v[r][j][1] * v[r][j][1]) + (v[r][j][2] * v[r][j][2] + v[r][j][3] * v[r][j][3]);
;             sq[r] = wave_sum(s); }
; #pragma unroll
;         for (int r = 0; r < 4; ++r) { u32x2* o8 = (u32x2*)(hb + (row + r) * D) + lane;
; #pragma unroll
;             for (int j = 0; j < 4; ++j) { u32x2 o; o.x = pk2(v[r][j][0], v[r][j][1]); o.y = pk2(v[r][j][2], v[r][j][3]); o8[64 * j] = o; }
;             if (lane < 16) ssq[(row + r) * 16 + lane] = lane == 0 ? sq[r] : 0.f; } }
	v_mul_f32_e32 v84, v9, v9
	v_mul_f32_e32 v87, v11, v11
	v_fmac_f32_e32 v89, v12, v12
	v_fmac_f32_e32 v91, v14, v14
	v_fmac_f32_e32 v84, v8, v8
	v_fmac_f32_e32 v87, v10, v10
	v_add_f32_e32 v72, v89, v91
	v_add_f32_e32 v84, v84, v87
	v_add_f32_e32 v72, v72, v84
	s_waitcnt vmcnt(1)
	v_mul_f32_e32 v84, v5, v5
	v_mul_f32_e32 v87, v7, v7
	v_fmac_f32_e32 v84, v4, v4
	v_fmac_f32_e32 v87, v6, v6
	v_add_f32_e32 v84, v84, v87
	v_mul_f32_e32 v98, v17, v17
	v_mul_f32_e32 v99, v19, v19
	v_add_f32_e32 v72, v72, v84
	s_waitcnt vmcnt(0)
	v_mul_f32_e32 v84, v1, v1
	v_mul_f32_e32 v87, v3, v3
	v_fmac_f32_e32 v98, v16, v16
	v_fmac_f32_e32 v99, v18, v18
	v_fmac_f32_e32 v84, v0, v0
	v_fmac_f32_e32 v87, v2, v2
	v_add_f32_e32 v90, v98, v99
	v_add_f32_e32 v84, v84, v87
	v_add_f32_e32 v73, v73, v90
	v_add_f32_e32 v72, v72, v84
	s_nop 1
	v_mov_b32_dpp v85, v83 quad_perm:[1,0,3,2] row_mask:0xf bank_mask:0xf
	s_nop 1
	v_mov_b32_dpp v86, v73 quad_perm:[1,0,3,2] row_mask:0xf bank_mask:0xf
	s_nop 1
	v_mov_b32_dpp v84, v72 quad_perm:[1,0,3,2] row_mask:0xf bank_mask:0xf
	v_mov_b32_e32 v90, v88
	v_mov_b32_e32 v100, v88
	s_nop 1
	v_permlane32_swap_b32_e32 v100, v90
	s_waitcnt lgkmcnt(3)
	v_add_f32_e32 v83, v83, v85
	s_waitcnt lgkmcnt(2)
	v_add_f32_e32 v73, v73, v86
	s_waitcnt lgkmcnt(1)
	v_add_f32_e32 v72, v72, v84
	s_nop 1
	v_mov_b32_dpp v85, v83 quad_perm:[2,3,0,1] row_mask:0xf bank_mask:0xf
	s_nop 1
	v_mov_b32_dpp v86, v73 quad_perm:[2,3,0,1] row_mask:0xf bank_mask:0xf
	s_nop 1
	v_mov_b32_dpp v84, v72 quad_perm:[2,3,0,1] row_mask:0xf bank_mask:0xf
	s_waitcnt lgkmcnt(2)
	v_add_f32_e32 v83, v83, v85
	s_waitcnt lgkmcnt(1)
	v_add_f32_e32 v73, v73, v86
	s_waitcnt lgkmcnt(0)
	v_add_f32_e32 v72, v72, v84
	s_nop 1
	v_mov_b32_dpp v100, v83 row_half_mirror row_mask:0xf bank_mask:0xf
	s_nop 1
	v_mov_b32_dpp v85, v100 quad_perm:[3,2,1,0] row_mask:0xf bank_mask:0xf
	s_nop 1
	v_mov_b32_dpp v100, v73 row_half_mirror row_mask:0xf bank_mask:0xf
	s_nop 1
	v_mov_b32_dpp v86, v100 quad_perm:[3,2,1,0] row_mask:0xf bank_mask:0xf
	s_nop 1
	v_mov_b32_dpp v100, v72 row_half_mirror row_mask:0xf bank_mask:0xf
	s_nop 1
	v_mov_b32_dpp v84, v100 quad_perm:[3,2,1,0] row_mask:0xf bank_mask:0xf
	s_waitcnt lgkmcnt(2)
	v_add_f32_e32 v83, v83, v85
	s_waitcnt lgkmcnt(1)
	v_add_f32_e32 v73, v73, v86
	s_waitcnt lgkmcnt(0)
	v_add_f32_e32 v72, v72, v84
	s_nop 1
	v_mov_b32_dpp v85, v83 row_ror:8 row_mask:0xf bank_mask:0xf
	s_nop 1
	v_mov_b32_dpp v86, v73 row_ror:8 row_mask:0xf bank_mask:0xf
	s_nop 1
	v_mov_b32_dpp v84, v72 row_ror:8 row_mask:0xf bank_mask:0xf
	s_waitcnt lgkmcnt(2)
	v_add_f32_e32 v83, v83, v85
	s_waitcnt lgkmcnt(1)
	v_add_f32_e32 v73, v73, v86
	s_waitcnt lgkmcnt(0)
	v_add_f32_e32 v72, v72, v84
	v_mov_b32_e32 v85, v83
	v_mov_b32_e32 v100, v83
	s_nop 1
	v_permlane16_swap_b32_e32 v100, v85
	v_mov_b32_e32 v86, v73
	v_mov_b32_e32 v100, v73
	s_nop 1
	v_permlane16_swap_b32_e32 v100, v86
	v_mov_b32_e32 v84, v72
	v_mov_b32_e32 v100, v72
	s_nop 1
	v_permlane16_swap_b32_e32 v100, v84
	s_waitcnt lgkmcnt(2)
	v_add_f32_e32 v87, v83, v85
	s_waitcnt lgkmcnt(1)
	v_add_f32_e32 v85, v73, v86
	s_waitcnt lgkmcnt(0)
	v_add_f32_e32 v83, v72, v84
	v_mov_b32_e32 v89, v87
	v_mov_b32_e32 v100, v87
	s_nop 1
	v_permlane32_swap_b32_e32 v100, v89
	v_mov_b32_e32 v86, v85
	v_mov_b32_e32 v100, v85
	s_nop 1
	v_permlane32_swap_b32_e32 v100, v86
	v_mov_b32_e32 v84, v83
	v_mov_b32_e32 v100, v83
	s_nop 1
	v_permlane32_swap_b32_e32 v100, v84
	v_lshl_add_u64 v[72:73], s[62:63], 0, v[70:71]
	v_add_co_u32_e32 v62, vcc, s3, v72
	s_nop 1
	v_addc_co_u32_e32 v63, vcc, 0, v73, vcc
	global_store_dwordx2 v[62:63], v[60:61], off
	v_cvt_pk_bf16_f32 v56, v56, v57
	v_cvt_pk_bf16_f32 v57, v58, v59
	global_store_dwordx2 v[62:63], v[56:57], off offset:512
	v_cvt_pk_bf16_f32 v52, v52, v53
	v_cvt_pk_bf16_f32 v53, v54, v55
	global_store_dwordx2 v[62:63], v[52:53], off offset:1024
	v_cvt_pk_bf16_f32 v48, v48, v49
	v_cvt_pk_bf16_f32 v49, v50, v51
	global_store_dwordx2 v[62:63], v[48:49], off offset:1536
	v_lshl_add_u64 v[48:49], s[62:63], 0, v[68:69]
	s_and_saveexec_b64 s[12:13], s[0:1]
	s_cbranch_execz .LBB0_75
	v_add_f32_e32 v50, v88, v90
	v_cndmask_b32_e64 v50, 0, v50, s[4:5]
	global_store_dword v[48:49], v50, off offset:-128
